# v13 + lazy-rescale GQA attention
# baseline (speedup 1.0000x reference)
; template <int DQ, bool NA, int NQG>
; DI void attn_wg(const half_t* Qp, const half_t* Kp, const half_t* Vp, int q0, bool active, int seg0_start, int seg0_tiles,
;                 int seg1_start, int seg1_tiles, const float* rpb_h, int rq, char* smem, int tid, f16v (&O)[2][NQG]) {
;     ...
;       for (int st = 0; st < 2; ++st) {
;         f16v S[NQG];
; #pragma unroll
;         for (int qg = 0; qg < NQG; ++qg)
; #pragma unroll
;           for (int i = 0; i < 16; ++i) S[qg][i] = 0.f;
; #pragma unroll
;         for (int ks = 0; ks < NKS; ++ks) {
;           const h8 kf = *(const h8*)(ksm + (st * 32) * KSTR + ks * 16);
; #pragma unroll
;           for (int qg = 0; qg < NQG; ++qg) S[qg] = __builtin_amdgcn_mfma_f32_32x32x16_f16(kf, qf[qg][ks], S[qg], 0, 0, 0);
;         }
;         if (masked) {
;           const int cb = st * 32;
;           const int dr = krow - rq + 7;
; #pragma unroll
;           for (int qg = 0; qg < NQG; ++qg) {
;             const int qc = qg * 32 + r;
;             const int cs = min(max(qc - 8, 0), 48);
; #pragma unroll
;             for (int i = 0; i < 16; ++i) {
;               const int c = cb + (i & 3) + 8 * (i >> 2) + 4 * h;
;               const bool valid = (c >= cs) && (c < cs + 16);
;               float bias = 0.f;
;               if (valid) bias = rpb_h[dr * 31 + (c - qc + 15)] * LOG2E;
;               S[qg][i] = valid ? S[qg][i] + bias : -1e30f;
;             }
;           }
;         }
;         h4 vf[2][2][2];
; #pragma unroll
;         for (int dvt = 0; dvt < 2; ++dvt)
; #pragma unroll
;           for (int sx = 0; sx < 2; ++sx)
; #pragma unroll
;             for (int hf = 0; hf < 2; ++hf) vf[dvt][sx][hf] = *(const h4*)(vsm + (dvt * 32) * VSTR + st * 32 + sx * 16 + hf * 8);
; #pragma unroll
;         for (int qg = 0; qg < NQG; ++qg) {
;           h8 P[2];
;           float mx = S[qg][0];
; #pragma unroll
;           for (int i = 1; i < 16; ++i) mx = fmaxf(mx, S[qg][i]);
;           mx = fmaxf(mx, __shfl_xor(mx, 32));
;           if (__builtin_amdgcn_ballot_w64(mx > mrun[qg] + 8.f) != 0ull) {
;             const float mnew = fmaxf(mrun[qg], mx);
;             const float alpha = __builtin_amdgcn_exp2f(mrun[qg] - mnew);
;             lrun[qg] *= alpha;
; #pragma unroll
;             for (int dvt = 0; dvt < 2; ++dvt)
; #pragma unroll
;               for (int i = 0; i < 16; ++i) O[dvt][qg][i] *= alpha;
;             mrun[qg] = mnew;
.LBB0_1917:
	v_cndmask_b32_e64 v66, 0, 1, s[14:15]
	v_cmp_ne_u32_e64 s[6:7], 1, v66
	s_andn2_b64 vcc, exec, s[14:15]
	s_cbranch_vccnz .LBB0_1924
	s_bitcmp1_b32 s22, 0
	s_cselect_b32 s22, 0x5800, 0
	v_add3_u32 v187, s22, v237, v156
	v_add3_u32 v189, s22, v237, v155
	v_add_u32_e32 v197, 0x4600, v189
	v_add_u32_e32 v189, 0x3400, v189
	ds_read_b128 v[198:201], v187 offset:0
	ds_read_b128 v[202:205], v187 offset:32
	ds_read_b128 v[206:209], v187 offset:64
	ds_read_b128 v[210:213], v187 offset:96
	ds_read2_b64 v[138:141], v189 offset0:0 offset1:2
	ds_read2_b64 v[142:145], v189 offset0:4 offset1:6
	ds_read2_b64 v[146:149], v197 offset0:0 offset1:2
	ds_read2_b64 v[150:153], v197 offset0:4 offset1:6
	s_waitcnt lgkmcnt(7)
	v_mfma_f32_32x32x16_f16 v[82:97], v[198:201], v[98:101], 0
	s_waitcnt lgkmcnt(6)
	v_mfma_f32_32x32x16_f16 v[82:97], v[202:205], v[102:105], v[82:97]
	s_waitcnt lgkmcnt(5)
	v_mfma_f32_32x32x16_f16 v[82:97], v[206:209], v[106:109], v[82:97]
	s_waitcnt lgkmcnt(4)
	v_mfma_f32_32x32x16_f16 v[82:97], v[210:213], v[110:113], v[82:97]
	s_nop 11
	v_pk_add_f32 v[82:83], v[82:83], v[194:195] op_sel_hi:[1,0] neg_lo:[0,1] neg_hi:[0,1]
	v_pk_add_f32 v[84:85], v[84:85], v[194:195] op_sel_hi:[1,0] neg_lo:[0,1] neg_hi:[0,1]
	v_exp_f32_e32 v82, v82
	v_exp_f32_e32 v83, v83
	v_pk_add_f32 v[86:87], v[86:87], v[194:195] op_sel_hi:[1,0] neg_lo:[0,1] neg_hi:[0,1]
	v_mfma_f32_32x32x16_f16 v[66:81], v[198:201], v[114:117], 0
	v_exp_f32_e32 v84, v84
	v_exp_f32_e32 v85, v85
	v_pk_add_f32 v[88:89], v[88:89], v[194:195] op_sel_hi:[1,0] neg_lo:[0,1] neg_hi:[0,1]
	v_exp_f32_e32 v86, v86
	v_exp_f32_e32 v87, v87
	v_pk_add_f32 v[90:91], v[90:91], v[194:195] op_sel_hi:[1,0] neg_lo:[0,1] neg_hi:[0,1]
	v_exp_f32_e32 v88, v88
	v_mfma_f32_32x32x16_f16 v[66:81], v[202:205], v[118:121], v[66:81]
	v_exp_f32_e32 v89, v89
	v_pk_add_f32 v[92:93], v[92:93], v[194:195] op_sel_hi:[1,0] neg_lo:[0,1] neg_hi:[0,1]
	v_exp_f32_e32 v90, v90
	v_exp_f32_e32 v91, v91
	v_pk_add_f32 v[94:95], v[94:95], v[194:195] op_sel_hi:[1,0] neg_lo:[0,1] neg_hi:[0,1]
	v_exp_f32_e32 v92, v92
	v_exp_f32_e32 v93, v93
	v_mfma_f32_32x32x16_f16 v[66:81], v[206:209], v[122:125], v[66:81]
	v_pk_add_f32 v[96:97], v[96:97], v[194:195] op_sel_hi:[1,0] neg_lo:[0,1] neg_hi:[0,1]
	v_exp_f32_e32 v94, v94
	v_exp_f32_e32 v95, v95
	v_exp_f32_e32 v96, v96
	v_exp_f32_e32 v97, v97
	v_cvt_pk_f16_f32 v214, v82, v83
	v_cvt_pk_f16_f32 v215, v84, v85
	v_mfma_f32_32x32x16_f16 v[66:81], v[210:213], v[126:129], v[66:81]
	v_cvt_pk_f16_f32 v216, v86, v87
	v_cvt_pk_f16_f32 v217, v88, v89
	v_cvt_pk_f16_f32 v218, v90, v91
	v_cvt_pk_f16_f32 v219, v92, v93
	v_cvt_pk_f16_f32 v220, v94, v95
	v_cvt_pk_f16_f32 v221, v96, v97
	v_pk_add_f32 v[222:223], v[82:83], v[84:85]
	v_pk_add_f32 v[224:225], v[86:87], v[88:89]
	v_pk_add_f32 v[226:227], v[90:91], v[92:93]
	v_pk_add_f32 v[228:229], v[94:95], v[96:97]
	v_pk_add_f32 v[222:223], v[222:223], v[224:225]
	v_pk_add_f32 v[226:227], v[226:227], v[228:229]
	v_pk_add_f32 v[222:223], v[222:223], v[226:227]
	v_add_f32_e32 v222, v222, v223
	v_cmp_lt_f32_e32 vcc, 0x43800000, v222
	s_cbranch_vccnz .Leager_gqa_0
.Lcont_gqa_0:
	v_add_f32_e32 v183, v183, v222
	ds_read_b128 v[198:201], v187 offset:4608
	ds_read_b128 v[202:205], v187 offset:4640
	ds_read_b128 v[206:209], v187 offset:4672
	ds_read_b128 v[210:213], v187 offset:4704
	v_pk_add_f32 v[66:67], v[66:67], v[196:197] op_sel_hi:[1,0] neg_lo:[0,1] neg_hi:[0,1]
	v_pk_add_f32 v[68:69], v[68:69], v[196:197] op_sel_hi:[1,0] neg_lo:[0,1] neg_hi:[0,1]
	v_exp_f32_e32 v66, v66
	s_waitcnt lgkmcnt(7)
	v_mfma_f32_32x32x16_f16 v[2:17], v[138:141], v[214:217], v[2:17]
	v_exp_f32_e32 v67, v67
	v_pk_add_f32 v[70:71], v[70:71], v[196:197] op_sel_hi:[1,0] neg_lo:[0,1] neg_hi:[0,1]
	v_exp_f32_e32 v68, v68
	v_exp_f32_e32 v69, v69
	v_pk_add_f32 v[72:73], v[72:73], v[196:197] op_sel_hi:[1,0] neg_lo:[0,1] neg_hi:[0,1]
	v_exp_f32_e32 v70, v70
	s_waitcnt lgkmcnt(5)
	v_mfma_f32_32x32x16_f16 v[18:33], v[146:149], v[214:217], v[18:33]
	v_exp_f32_e32 v71, v71
	v_pk_add_f32 v[74:75], v[74:75], v[196:197] op_sel_hi:[1,0] neg_lo:[0,1] neg_hi:[0,1]
	v_exp_f32_e32 v72, v72
	v_exp_f32_e32 v73, v73
	v_pk_add_f32 v[76:77], v[76:77], v[196:197] op_sel_hi:[1,0] neg_lo:[0,1] neg_hi:[0,1]
	v_mfma_f32_32x32x16_f16 v[2:17], v[142:145], v[218:221], v[2:17]
	v_exp_f32_e32 v74, v74
	v_exp_f32_e32 v75, v75
	v_pk_add_f32 v[78:79], v[78:79], v[196:197] op_sel_hi:[1,0] neg_lo:[0,1] neg_hi:[0,1]
	v_exp_f32_e32 v76, v76
	v_exp_f32_e32 v77, v77
	v_pk_add_f32 v[80:81], v[80:81], v[196:197] op_sel_hi:[1,0] neg_lo:[0,1] neg_hi:[0,1]
	s_waitcnt lgkmcnt(4)
	v_mfma_f32_32x32x16_f16 v[18:33], v[150:153], v[218:221], v[18:33]
	v_exp_f32_e32 v78, v78
	v_exp_f32_e32 v79, v79
	v_exp_f32_e32 v80, v80
	s_waitcnt lgkmcnt(3)
	v_mfma_f32_32x32x16_f16 v[82:97], v[198:201], v[98:101], 0
	v_exp_f32_e32 v81, v81
	v_cvt_pk_f16_f32 v214, v66, v67
	s_waitcnt lgkmcnt(2)
	v_mfma_f32_32x32x16_f16 v[82:97], v[202:205], v[102:105], v[82:97]
	v_cvt_pk_f16_f32 v215, v68, v69
	v_cvt_pk_f16_f32 v216, v70, v71
	s_waitcnt lgkmcnt(1)
	v_mfma_f32_32x32x16_f16 v[82:97], v[206:209], v[106:109], v[82:97]
	v_cvt_pk_f16_f32 v217, v72, v73
	v_cvt_pk_f16_f32 v218, v74, v75
	s_waitcnt lgkmcnt(0)
	v_mfma_f32_32x32x16_f16 v[82:97], v[210:213], v[110:113], v[82:97]
	v_cvt_pk_f16_f32 v219, v76, v77
	v_cvt_pk_f16_f32 v220, v78, v79
	v_cvt_pk_f16_f32 v221, v80, v81
	v_pk_add_f32 v[222:223], v[66:67], v[68:69]
	v_pk_add_f32 v[224:225], v[70:71], v[72:73]
	v_pk_add_f32 v[226:227], v[74:75], v[76:77]
	v_pk_add_f32 v[228:229], v[78:79], v[80:81]
	v_pk_add_f32 v[222:223], v[222:223], v[224:225]
	v_pk_add_f32 v[226:227], v[226:227], v[228:229]
	v_pk_add_f32 v[222:223], v[222:223], v[226:227]
	v_add_f32_e32 v222, v222, v223
	v_cmp_lt_f32_e32 vcc, 0x43800000, v222
	s_cbranch_vccnz .Leager_gqa_1
; template <int DQ, bool NA, int NQG>
; DI void attn_wg(const half_t* Qp, const half_t* Kp, const half_t* Vp, int q0, bool active, int seg0_start, int seg0_tiles,
;                 int seg1_start, int seg1_tiles, const float* rpb_h, int rq, char* smem, int tid, f16v (&O)[2][NQG]) {
;     ...
;       for (int st = 0; st < 2; ++st) {
;         f16v S[NQG];
; #pragma unroll
;         for (int qg = 0; qg < NQG; ++qg)
; #pragma unroll
;           for (int i = 0; i < 16; ++i) S[qg][i] = 0.f;
; #pragma unroll
;         for (int ks = 0; ks < NKS; ++ks) {
;           const h8 kf = *(const h8*)(ksm + (st * 32) * KSTR + ks * 16);
; #pragma unroll
;           for (int qg = 0; qg < NQG; ++qg) S[qg] = __builtin_amdgcn_mfma_f32_32x32x16_f16(kf, qf[qg][ks], S[qg], 0, 0, 0);
;         }
;         if (masked) {
;           const int cb = st * 32;
;           const int dr = krow - rq + 7;
; #pragma unroll
;           for (int qg = 0; qg < NQG; ++qg) {
;             const int qc = qg * 32 + r;
;             const int cs = min(max(qc - 8, 0), 48);
; #pragma unroll
;             for (int i = 0; i < 16; ++i) {
;               const int c = cb + (i & 3) + 8 * (i >> 2) + 4 * h;
;               const bool valid = (c >= cs) && (c < cs + 16);
;               float bias = 0.f;
;               if (valid) bias = rpb_h[dr * 31 + (c - qc + 15)] * LOG2E;
;               S[qg][i] = valid ? S[qg][i] + bias : -1e30f;
;             }
;           }
;         }
;         h4 vf[2][2][2];
; #pragma unroll
;         for (int dvt = 0; dvt < 2; ++dvt)
; #pragma unroll
;           for (int sx = 0; sx < 2; ++sx)
; #pragma unroll
;             for (int hf = 0; hf < 2; ++hf) vf[dvt][sx][hf] = *(const h4*)(vsm + (dvt * 32) * VSTR + st * 32 + sx * 16 + hf * 8);
; #pragma unroll
;         for (int qg = 0; qg < NQG; ++qg) {
;           h8 P[2];
;           float mx = S[qg][0];
; #pragma unroll
;           for (int i = 1; i < 16; ++i) mx = fmaxf(mx, S[qg][i]);
;           mx = fmaxf(mx, __shfl_xor(mx, 32));
;           if (__builtin_amdgcn_ballot_w64(mx > mrun[qg] + 8.f) != 0ull) {
;             const float mnew = fmaxf(mrun[qg], mx);
;             const float alpha = __builtin_amdgcn_exp2f(mrun[qg] - mnew);
;             lrun[qg] *= alpha;
; #pragma unroll
;             for (int dvt = 0; dvt < 2; ++dvt)
; #pragma unroll
;               for (int i = 0; i < 16; ++i) O[dvt][qg][i] *= alpha;
;             mrun[qg] = mnew;
.Lcont_gqa_1:
	v_add_f32_e32 v1, v1, v222
	v_pk_add_f32 v[82:83], v[82:83], v[194:195] op_sel_hi:[1,0] neg_lo:[0,1] neg_hi:[0,1]
	v_pk_add_f32 v[84:85], v[84:85], v[194:195] op_sel_hi:[1,0] neg_lo:[0,1] neg_hi:[0,1]
	v_exp_f32_e32 v82, v82
	v_mfma_f32_32x32x16_f16 v[34:49], v[138:141], v[214:217], v[34:49]
	v_exp_f32_e32 v83, v83
	v_pk_add_f32 v[86:87], v[86:87], v[194:195] op_sel_hi:[1,0] neg_lo:[0,1] neg_hi:[0,1]
	v_exp_f32_e32 v84, v84
	v_exp_f32_e32 v85, v85
	v_pk_add_f32 v[88:89], v[88:89], v[194:195] op_sel_hi:[1,0] neg_lo:[0,1] neg_hi:[0,1]
	v_exp_f32_e32 v86, v86
	v_mfma_f32_32x32x16_f16 v[50:65], v[146:149], v[214:217], v[50:65]
	v_exp_f32_e32 v87, v87
	v_pk_add_f32 v[90:91], v[90:91], v[194:195] op_sel_hi:[1,0] neg_lo:[0,1] neg_hi:[0,1]
	v_exp_f32_e32 v88, v88
	v_exp_f32_e32 v89, v89
	v_pk_add_f32 v[92:93], v[92:93], v[194:195] op_sel_hi:[1,0] neg_lo:[0,1] neg_hi:[0,1]
	v_mfma_f32_32x32x16_f16 v[34:49], v[142:145], v[218:221], v[34:49]
	v_exp_f32_e32 v90, v90
	v_exp_f32_e32 v91, v91
	v_pk_add_f32 v[94:95], v[94:95], v[194:195] op_sel_hi:[1,0] neg_lo:[0,1] neg_hi:[0,1]
	v_exp_f32_e32 v92, v92
	v_exp_f32_e32 v93, v93
	v_pk_add_f32 v[96:97], v[96:97], v[194:195] op_sel_hi:[1,0] neg_lo:[0,1] neg_hi:[0,1]
	v_mfma_f32_32x32x16_f16 v[50:65], v[150:153], v[218:221], v[50:65]
	ds_read2_b64 v[138:141], v189 offset0:8 offset1:10
	ds_read2_b64 v[142:145], v189 offset0:12 offset1:14
	ds_read2_b64 v[146:149], v197 offset0:8 offset1:10
	ds_read2_b64 v[150:153], v197 offset0:12 offset1:14
	v_exp_f32_e32 v94, v94
	v_exp_f32_e32 v95, v95
	v_exp_f32_e32 v96, v96
	v_mfma_f32_32x32x16_f16 v[66:81], v[198:201], v[114:117], 0
	v_exp_f32_e32 v97, v97
	v_cvt_pk_f16_f32 v214, v82, v83
	v_mfma_f32_32x32x16_f16 v[66:81], v[202:205], v[118:121], v[66:81]
	v_cvt_pk_f16_f32 v215, v84, v85
	v_cvt_pk_f16_f32 v216, v86, v87
	v_mfma_f32_32x32x16_f16 v[66:81], v[206:209], v[122:125], v[66:81]
	v_cvt_pk_f16_f32 v217, v88, v89
	v_cvt_pk_f16_f32 v218, v90, v91
	v_mfma_f32_32x32x16_f16 v[66:81], v[210:213], v[126:129], v[66:81]
	v_cvt_pk_f16_f32 v219, v92, v93
	v_cvt_pk_f16_f32 v220, v94, v95
	v_cvt_pk_f16_f32 v221, v96, v97
	v_pk_add_f32 v[222:223], v[82:83], v[84:85]
	v_pk_add_f32 v[224:225], v[86:87], v[88:89]
	v_pk_add_f32 v[226:227], v[90:91], v[92:93]
	v_pk_add_f32 v[228:229], v[94:95], v[96:97]
	v_pk_add_f32 v[222:223], v[222:223], v[224:225]
	v_pk_add_f32 v[226:227], v[226:227], v[228:229]
	v_pk_add_f32 v[222:223], v[222:223], v[226:227]
	v_add_f32_e32 v222, v222, v223
	v_cmp_lt_f32_e32 vcc, 0x43800000, v222
	s_cbranch_vccnz .Leager_gqa_2
.Lcont_gqa_2:
	v_add_f32_e32 v183, v183, v222
	v_pk_add_f32 v[66:67], v[66:67], v[196:197] op_sel_hi:[1,0] neg_lo:[0,1] neg_hi:[0,1]
	v_pk_add_f32 v[68:69], v[68:69], v[196:197] op_sel_hi:[1,0] neg_lo:[0,1] neg_hi:[0,1]
	v_exp_f32_e32 v66, v66
	s_waitcnt lgkmcnt(3)
	v_mfma_f32_32x32x16_f16 v[2:17], v[138:141], v[214:217], v[2:17]
	v_exp_f32_e32 v67, v67
	v_pk_add_f32 v[70:71], v[70:71], v[196:197] op_sel_hi:[1,0] neg_lo:[0,1] neg_hi:[0,1]
	v_exp_f32_e32 v68, v68
	v_exp_f32_e32 v69, v69
	v_pk_add_f32 v[72:73], v[72:73], v[196:197] op_sel_hi:[1,0] neg_lo:[0,1] neg_hi:[0,1]
	v_exp_f32_e32 v70, v70
	s_waitcnt lgkmcnt(1)
	v_mfma_f32_32x32x16_f16 v[18:33], v[146:149], v[214:217], v[18:33]
	v_exp_f32_e32 v71, v71
	v_pk_add_f32 v[74:75], v[74:75], v[196:197] op_sel_hi:[1,0] neg_lo:[0,1] neg_hi:[0,1]
	v_exp_f32_e32 v72, v72
	v_exp_f32_e32 v73, v73
	v_pk_add_f32 v[76:77], v[76:77], v[196:197] op_sel_hi:[1,0] neg_lo:[0,1] neg_hi:[0,1]
	v_mfma_f32_32x32x16_f16 v[2:17], v[142:145], v[218:221], v[2:17]
	v_exp_f32_e32 v74, v74
	v_exp_f32_e32 v75, v75
	v_pk_add_f32 v[78:79], v[78:79], v[196:197] op_sel_hi:[1,0] neg_lo:[0,1] neg_hi:[0,1]
	v_exp_f32_e32 v76, v76
	v_exp_f32_e32 v77, v77
	v_pk_add_f32 v[80:81], v[80:81], v[196:197] op_sel_hi:[1,0] neg_lo:[0,1] neg_hi:[0,1]
	s_waitcnt lgkmcnt(0)
	v_mfma_f32_32x32x16_f16 v[18:33], v[150:153], v[218:221], v[18:33]
	v_exp_f32_e32 v78, v78
	v_exp_f32_e32 v79, v79
	v_exp_f32_e32 v80, v80
	v_exp_f32_e32 v81, v81
	v_cvt_pk_f16_f32 v214, v66, v67
	v_cvt_pk_f16_f32 v215, v68, v69
	v_cvt_pk_f16_f32 v216, v70, v71
	v_cvt_pk_f16_f32 v217, v72, v73
	v_cvt_pk_f16_f32 v218, v74, v75
	v_cvt_pk_f16_f32 v219, v76, v77
	v_cvt_pk_f16_f32 v220, v78, v79
	v_cvt_pk_f16_f32 v221, v80, v81
	v_pk_add_f32 v[222:223], v[66:67], v[68:69]
	v_pk_add_f32 v[224:225], v[70:71], v[72:73]
	v_pk_add_f32 v[226:227], v[74:75], v[76:77]
	v_pk_add_f32 v[228:229], v[78:79], v[80:81]
	v_pk_add_f32 v[222:223], v[222:223], v[224:225]
	v_pk_add_f32 v[226:227], v[226:227], v[228:229]
	v_pk_add_f32 v[222:223], v[222:223], v[226:227]
	v_add_f32_e32 v222, v222, v223
	v_cmp_lt_f32_e32 vcc, 0x43800000, v222
	s_cbranch_vccnz .Leager_gqa_3
.Lcont_gqa_3:
	v_add_f32_e32 v1, v1, v222
	v_mfma_f32_32x32x16_f16 v[34:49], v[138:141], v[214:217], v[34:49]
	v_mfma_f32_32x32x16_f16 v[50:65], v[146:149], v[214:217], v[50:65]
	v_mfma_f32_32x32x16_f16 v[34:49], v[142:145], v[218:221], v[34:49]
	v_mfma_f32_32x32x16_f16 v[50:65], v[150:153], v[218:221], v[50:65]
	s_branch .Lend_gqa
; template <int DQ, bool NA, int NQG>
; DI void attn_wg(const half_t* Qp, const half_t* Kp, const half_t* Vp, int q0, bool active, int seg0_start, int seg0_tiles,
;                 int seg1_start, int seg1_tiles, const float* rpb_h, int rq, char* smem, int tid, f16v (&O)[2][NQG]) {
;     ...
;       for (int st = 0; st < 2; ++st) {
;         f16v S[NQG];
; #pragma unroll
;         for (int qg = 0; qg < NQG; ++qg)
; #pragma unroll
;           for (int i = 0; i < 16; ++i) S[qg][i] = 0.f;
; #pragma unroll
;         for (int ks = 0; ks < NKS; ++ks) {
;           const h8 kf = *(const h8*)(ksm + (st * 32) * KSTR + ks * 16);
; #pragma unroll
;           for (int qg = 0; qg < NQG; ++qg) S[qg] = __builtin_amdgcn_mfma_f32_32x32x16_f16(kf, qf[qg][ks], S[qg], 0, 0, 0);
;         }
;         if (masked) {
;           const int cb = st * 32;
;           const int dr = krow - rq + 7;
; #pragma unroll
;           for (int qg = 0; qg < NQG; ++qg) {
;             const int qc = qg * 32 + r;
;             const int cs = min(max(qc - 8, 0), 48);
; #pragma unroll
;             for (int i = 0; i < 16; ++i) {
;               const int c = cb + (i & 3) + 8 * (i >> 2) + 4 * h;
;               const bool valid = (c >= cs) && (c < cs + 16);
;               float bias = 0.f;
;               if (valid) bias = rpb_h[dr * 31 + (c - qc + 15)] * LOG2E;
;               S[qg][i] = valid ? S[qg][i] + bias : -1e30f;
;             }
;           }
;         }
;         h4 vf[2][2][2];
; #pragma unroll
;         for (int dvt = 0; dvt < 2; ++dvt)
; #pragma unroll
;           for (int sx = 0; sx < 2; ++sx)
; #pragma unroll
;             for (int hf = 0; hf < 2; ++hf) vf[dvt][sx][hf] = *(const h4*)(vsm + (dvt * 32) * VSTR + st * 32 + sx * 16 + hf * 8);
; #pragma unroll
;         for (int qg = 0; qg < NQG; ++qg) {
;           h8 P[2];
;           float mx = S[qg][0];
; #pragma unroll
;           for (int i = 1; i < 16; ++i) mx = fmaxf(mx, S[qg][i]);
;           mx = fmaxf(mx, __shfl_xor(mx, 32));
;           if (__builtin_amdgcn_ballot_w64(mx > mrun[qg] + 8.f) != 0ull) {
;             const float mnew = fmaxf(mrun[qg], mx);
;             const float alpha = __builtin_amdgcn_exp2f(mrun[qg] - mnew);
;             lrun[qg] *= alpha;
; #pragma unroll
;             for (int dvt = 0; dvt < 2; ++dvt)
; #pragma unroll
;               for (int i = 0; i < 16; ++i) O[dvt][qg][i] *= alpha;
;             mrun[qg] = mnew;
.Leager_gqa_0:
	s_nop 7
	v_mfma_f32_32x32x16_f16 v[82:97], v[198:201], v[98:101], 0
	v_mfma_f32_32x32x16_f16 v[82:97], v[202:205], v[102:105], v[82:97]
	v_mfma_f32_32x32x16_f16 v[82:97], v[206:209], v[106:109], v[82:97]
	v_mfma_f32_32x32x16_f16 v[82:97], v[210:213], v[110:113], v[82:97]
	s_nop 15
	s_nop 15
	v_max3_f32 v232, v82, v83, v84
	v_max3_f32 v233, v85, v86, v87
	v_max3_f32 v232, v232, v88, v89
	v_max3_f32 v232, v232, v92, v93
	v_max3_f32 v232, v232, v96, v97
	v_max3_f32 v233, v233, v90, v91
	v_max3_f32 v233, v233, v94, v95
	v_max_f32_e32 v232, v232, v233
	v_mov_b32_e32 v233, v232
	s_nop 1
	v_permlane32_swap_b32_e32 v233, v232
	v_max_f32_e32 v232, v232, v233
	v_max_f32_e32 v233, v194, v232
	v_sub_f32_e32 v230, v194, v233
	v_exp_f32_e32 v230, v230
	v_mov_b32_e32 v194, v233
	v_mul_f32_e32 v183, v183, v230
	v_pk_mul_f32 v[2:3], v[2:3], v[230:231] op_sel_hi:[1,0]
	v_pk_mul_f32 v[4:5], v[4:5], v[230:231] op_sel_hi:[1,0]
	v_pk_mul_f32 v[6:7], v[6:7], v[230:231] op_sel_hi:[1,0]
	v_pk_mul_f32 v[8:9], v[8:9], v[230:231] op_sel_hi:[1,0]
	v_pk_mul_f32 v[10:11], v[10:11], v[230:231] op_sel_hi:[1,0]
	v_pk_mul_f32 v[12:13], v[12:13], v[230:231] op_sel_hi:[1,0]
	v_pk_mul_f32 v[14:15], v[14:15], v[230:231] op_sel_hi:[1,0]
	v_pk_mul_f32 v[16:17], v[16:17], v[230:231] op_sel_hi:[1,0]
	v_pk_mul_f32 v[18:19], v[18:19], v[230:231] op_sel_hi:[1,0]
	v_pk_mul_f32 v[20:21], v[20:21], v[230:231] op_sel_hi:[1,0]
	v_pk_mul_f32 v[22:23], v[22:23], v[230:231] op_sel_hi:[1,0]
	v_pk_mul_f32 v[24:25], v[24:25], v[230:231] op_sel_hi:[1,0]
	v_pk_mul_f32 v[26:27], v[26:27], v[230:231] op_sel_hi:[1,0]
	v_pk_mul_f32 v[28:29], v[28:29], v[230:231] op_sel_hi:[1,0]
	v_pk_mul_f32 v[30:31], v[30:31], v[230:231] op_sel_hi:[1,0]
	v_pk_mul_f32 v[32:33], v[32:33], v[230:231] op_sel_hi:[1,0]
	v_pk_add_f32 v[82:83], v[82:83], v[194:195] op_sel_hi:[1,0] neg_lo:[0,1] neg_hi:[0,1]
	v_pk_add_f32 v[84:85], v[84:85], v[194:195] op_sel_hi:[1,0] neg_lo:[0,1] neg_hi:[0,1]
	v_pk_add_f32 v[86:87], v[86:87], v[194:195] op_sel_hi:[1,0] neg_lo:[0,1] neg_hi:[0,1]
	v_pk_add_f32 v[88:89], v[88:89], v[194:195] op_sel_hi:[1,0] neg_lo:[0,1] neg_hi:[0,1]
	v_pk_add_f32 v[90:91], v[90:91], v[194:195] op_sel_hi:[1,0] neg_lo:[0,1] neg_hi:[0,1]
	v_pk_add_f32 v[92:93], v[92:93], v[194:195] op_sel_hi:[1,0] neg_lo:[0,1] neg_hi:[0,1]
	v_pk_add_f32 v[94:95], v[94:95], v[194:195] op_sel_hi:[1,0] neg_lo:[0,1] neg_hi:[0,1]
	v_pk_add_f32 v[96:97], v[96:97], v[194:195] op_sel_hi:[1,0] neg_lo:[0,1] neg_hi:[0,1]
	v_exp_f32_e32 v82, v82
	v_exp_f32_e32 v83, v83
	v_exp_f32_e32 v84, v84
	v_exp_f32_e32 v85, v85
	v_exp_f32_e32 v86, v86
	v_exp_f32_e32 v87, v87
	v_exp_f32_e32 v88, v88
	v_exp_f32_e32 v89, v89
	v_exp_f32_e32 v90, v90
	v_exp_f32_e32 v91, v91
	v_exp_f32_e32 v92, v92
	v_exp_f32_e32 v93, v93
	v_exp_f32_e32 v94, v94
	v_exp_f32_e32 v95, v95
	v_exp_f32_e32 v96, v96
	v_exp_f32_e32 v97, v97
	s_nop 0
	v_cvt_pk_f16_f32 v214, v82, v83
	v_cvt_pk_f16_f32 v215, v84, v85
	v_cvt_pk_f16_f32 v216, v86, v87
	v_cvt_pk_f16_f32 v217, v88, v89
	v_cvt_pk_f16_f32 v218, v90, v91
	v_cvt_pk_f16_f32 v219, v92, v93
	v_cvt_pk_f16_f32 v220, v94, v95
	v_cvt_pk_f16_f32 v221, v96, v97
	v_pk_add_f32 v[222:223], v[82:83], v[84:85]
	v_pk_add_f32 v[224:225], v[86:87], v[88:89]
	v_pk_add_f32 v[226:227], v[90:91], v[92:93]
	v_pk_add_f32 v[228:229], v[94:95], v[96:97]
	v_pk_add_f32 v[222:223], v[222:223], v[224:225]
	v_pk_add_f32 v[226:227], v[226:227], v[228:229]
	v_pk_add_f32 v[222:223], v[222:223], v[226:227]
	v_add_f32_e32 v222, v222, v223
	s_branch .Lcont_gqa_0
; template <int DQ, bool NA, int NQG>
; DI void attn_wg(const half_t* Qp, const half_t* Kp, const half_t* Vp, int q0, bool active, int seg0_start, int seg0_tiles,
;                 int seg1_start, int seg1_tiles, const float* rpb_h, int rq, char* smem, int tid, f16v (&O)[2][NQG]) {
;     ...
;         for (int ks = 0; ks < NKS; ++ks) {
;           const h8 kf = *(const h8*)(ksm + (st * 32) * KSTR + ks * 16);
; #pragma unroll
;           for (int qg = 0; qg < NQG; ++qg) S[qg] = __builtin_amdgcn_mfma_f32_32x32x16_f16(kf, qf[qg][ks], S[qg], 0, 0, 0);
;         }
;     ...
;         for (int qg = 0; qg < NQG; ++qg) {
;           h8 P[2];
;           float mx = S[qg][0];
; #pragma unroll
;           for (int i = 1; i < 16; ++i) mx = fmaxf(mx, S[qg][i]);
;           mx = fmaxf(mx, __shfl_xor(mx, 32));
;           if (__builtin_amdgcn_ballot_w64(mx > mrun[qg] + 8.f) != 0ull) {
;             const float mnew = fmaxf(mrun[qg], mx);
;             const float alpha = __builtin_amdgcn_exp2f(mrun[qg] - mnew);
;             lrun[qg] *= alpha;
; #pragma unroll
;             for (int dvt = 0; dvt < 2; ++dvt)
; #pragma unroll
;               for (int i = 0; i < 16; ++i) O[dvt][qg][i] *= alpha;
;             mrun[qg] = mnew;
;           }
;           const float mn = mrun[qg];
;           f2 rs2 = {0.f, 0.f};
;           const f2 mn2 = {mn, mn};
; #pragma unroll
;           for (int i = 0; i < 16; i += 2) {
;             const f2 s2 = {S[qg][i], S[qg][i + 1]};
;             const f2 d2 = s2 - mn2;
;             f2 p2;
;             p2.x = __builtin_amdgcn_exp2f(d2.x);
;             p2.y = __builtin_amdgcn_exp2f(d2.y);
;             if (NA) { p2.x = (s2.x <= -1e29f) ? 0.f : p2.x; p2.y = (s2.y <= -1e29f) ? 0.f : p2.y; }
;             rs2 += p2;
;             P[i >> 3][i & 7] = (half_t)p2.x;
;             P[i >> 3][(i & 7) + 1] = (half_t)p2.y;
;           }
;           lrun[qg] += rs2.x + rs2.y;
.Leager_gqa_1:
	ds_read_b128 v[198:201], v187 offset:0
	ds_read_b128 v[202:205], v187 offset:32
	ds_read_b128 v[206:209], v187 offset:64
	ds_read_b128 v[210:213], v187 offset:96
	s_waitcnt lgkmcnt(0)
	s_nop 7
	v_mfma_f32_32x32x16_f16 v[66:81], v[198:201], v[114:117], 0
	v_mfma_f32_32x32x16_f16 v[66:81], v[202:205], v[118:121], v[66:81]
	v_mfma_f32_32x32x16_f16 v[66:81], v[206:209], v[122:125], v[66:81]
	v_mfma_f32_32x32x16_f16 v[66:81], v[210:213], v[126:129], v[66:81]
	s_nop 15
	s_nop 15
	v_max3_f32 v232, v66, v67, v68
	v_max3_f32 v233, v69, v70, v71
	v_max3_f32 v232, v232, v72, v73
	v_max3_f32 v232, v232, v76, v77
	v_max3_f32 v232, v232, v80, v81
	v_max3_f32 v233, v233, v74, v75
	v_max3_f32 v233, v233, v78, v79
	v_max_f32_e32 v232, v232, v233
	v_mov_b32_e32 v233, v232
	s_nop 1
	v_permlane32_swap_b32_e32 v233, v232
	v_max_f32_e32 v232, v232, v233
	ds_read_b128 v[198:201], v187 offset:4608
	ds_read_b128 v[202:205], v187 offset:4640
	ds_read_b128 v[206:209], v187 offset:4672
	ds_read_b128 v[210:213], v187 offset:4704
	v_max_f32_e32 v233, v196, v232
	v_sub_f32_e32 v230, v196, v233
	v_exp_f32_e32 v230, v230
	v_mov_b32_e32 v196, v233
	v_mul_f32_e32 v1, v1, v230
	v_pk_mul_f32 v[34:35], v[34:35], v[230:231] op_sel_hi:[1,0]
	v_pk_mul_f32 v[36:37], v[36:37], v[230:231] op_sel_hi:[1,0]
	v_pk_mul_f32 v[38:39], v[38:39], v[230:231] op_sel_hi:[1,0]
	v_pk_mul_f32 v[40:41], v[40:41], v[230:231] op_sel_hi:[1,0]
	v_pk_mul_f32 v[42:43], v[42:43], v[230:231] op_sel_hi:[1,0]
	v_pk_mul_f32 v[44:45], v[44:45], v[230:231] op_sel_hi:[1,0]
	v_pk_mul_f32 v[46:47], v[46:47], v[230:231] op_sel_hi:[1,0]
	v_pk_mul_f32 v[48:49], v[48:49], v[230:231] op_sel_hi:[1,0]
	v_pk_mul_f32 v[50:51], v[50:51], v[230:231] op_sel_hi:[1,0]
	v_pk_mul_f32 v[52:53], v[52:53], v[230:231] op_sel_hi:[1,0]
	v_pk_mul_f32 v[54:55], v[54:55], v[230:231] op_sel_hi:[1,0]
	v_pk_mul_f32 v[56:57], v[56:57], v[230:231] op_sel_hi:[1,0]
	v_pk_mul_f32 v[58:59], v[58:59], v[230:231] op_sel_hi:[1,0]
	v_pk_mul_f32 v[60:61], v[60:61], v[230:231] op_sel_hi:[1,0]
	v_pk_mul_f32 v[62:63], v[62:63], v[230:231] op_sel_hi:[1,0]
	v_pk_mul_f32 v[64:65], v[64:65], v[230:231] op_sel_hi:[1,0]
	v_pk_add_f32 v[66:67], v[66:67], v[196:197] op_sel_hi:[1,0] neg_lo:[0,1] neg_hi:[0,1]
	v_pk_add_f32 v[68:69], v[68:69], v[196:197] op_sel_hi:[1,0] neg_lo:[0,1] neg_hi:[0,1]
	v_pk_add_f32 v[70:71], v[70:71], v[196:197] op_sel_hi:[1,0] neg_lo:[0,1] neg_hi:[0,1]
	v_pk_add_f32 v[72:73], v[72:73], v[196:197] op_sel_hi:[1,0] neg_lo:[0,1] neg_hi:[0,1]
	v_pk_add_f32 v[74:75], v[74:75], v[196:197] op_sel_hi:[1,0] neg_lo:[0,1] neg_hi:[0,1]
	v_pk_add_f32 v[76:77], v[76:77], v[196:197] op_sel_hi:[1,0] neg_lo:[0,1] neg_hi:[0,1]
	v_pk_add_f32 v[78:79], v[78:79], v[196:197] op_sel_hi:[1,0] neg_lo:[0,1] neg_hi:[0,1]
	v_pk_add_f32 v[80:81], v[80:81], v[196:197] op_sel_hi:[1,0] neg_lo:[0,1] neg_hi:[0,1]
	v_exp_f32_e32 v66, v66
	v_exp_f32_e32 v67, v67
	v_exp_f32_e32 v68, v68
	v_exp_f32_e32 v69, v69
	v_exp_f32_e32 v70, v70
	v_exp_f32_e32 v71, v71
	v_exp_f32_e32 v72, v72
	v_exp_f32_e32 v73, v73
	v_exp_f32_e32 v74, v74
	v_exp_f32_e32 v75, v75
	v_exp_f32_e32 v76, v76
	v_exp_f32_e32 v77, v77
	v_exp_f32_e32 v78, v78
	v_exp_f32_e32 v79, v79
	v_exp_f32_e32 v80, v80
	v_exp_f32_e32 v81, v81
	s_nop 0
	v_cvt_pk_f16_f32 v214, v66, v67
	v_cvt_pk_f16_f32 v215, v68, v69
	v_cvt_pk_f16_f32 v216, v70, v71
	v_cvt_pk_f16_f32 v217, v72, v73
	v_cvt_pk_f16_f32 v218, v74, v75
	v_cvt_pk_f16_f32 v219, v76, v77
	v_cvt_pk_f16_f32 v220, v78, v79
	v_cvt_pk_f16_f32 v221, v80, v81
	v_pk_add_f32 v[222:223], v[66:67], v[68:69]
	v_pk_add_f32 v[224:225], v[70:71], v[72:73]
	v_pk_add_f32 v[226:227], v[74:75], v[76:77]
	v_pk_add_f32 v[228:229], v[78:79], v[80:81]
	v_pk_add_f32 v[222:223], v[222:223], v[224:225]
	v_pk_add_f32 v[226:227], v[226:227], v[228:229]
	v_pk_add_f32 v[222:223], v[222:223], v[226:227]
	v_add_f32_e32 v222, v222, v223
	s_waitcnt lgkmcnt(0)
	s_branch .Lcont_gqa_1

; template <int DQ, bool NA, int NQG>
; DI void attn_wg(const half_t* Qp, const half_t* Kp, const half_t* Vp, int q0, bool active, int seg0_start, int seg0_tiles,
;                 int seg1_start, int seg1_tiles, const float* rpb_h, int rq, char* smem, int tid, f16v (&O)[2][NQG]) {
;     ...
;         for (int ks = 0; ks < NKS; ++ks) {
;           const h8 kf = *(const h8*)(ksm + (st * 32) * KSTR + ks * 16);
; #pragma unroll
;           for (int qg = 0; qg < NQG; ++qg) S[qg] = __builtin_amdgcn_mfma_f32_32x32x16_f16(kf, qf[qg][ks], S[qg], 0, 0, 0);
;         }
;     ...
;         for (int qg = 0; qg < NQG; ++qg) {
;           h8 P[2];
;           float mx = S[qg][0];
; #pragma unroll
;           for (int i = 1; i < 16; ++i) mx = fmaxf(mx, S[qg][i]);
;           mx = fmaxf(mx, __shfl_xor(mx, 32));
;           if (__builtin_amdgcn_ballot_w64(mx > mrun[qg] + 8.f) != 0ull) {
;             const float mnew = fmaxf(mrun[qg], mx);
;             const float alpha = __builtin_amdgcn_exp2f(mrun[qg] - mnew);
;             lrun[qg] *= alpha;
; #pragma unroll
;             for (int dvt = 0; dvt < 2; ++dvt)
; #pragma unroll
;               for (int i = 0; i < 16; ++i) O[dvt][qg][i] *= alpha;
;             mrun[qg] = mnew;
;           }
;           const float mn = mrun[qg];
;           f2 rs2 = {0.f, 0.f};
;           const f2 mn2 = {mn, mn};
; #pragma unroll
;           for (int i = 0; i < 16; i += 2) {
;             const f2 s2 = {S[qg][i], S[qg][i + 1]};
;             const f2 d2 = s2 - mn2;
;             f2 p2;
;             p2.x = __builtin_amdgcn_exp2f(d2.x);
;             p2.y = __builtin_amdgcn_exp2f(d2.y);
;             if (NA) { p2.x = (s2.x <= -1e29f) ? 0.f : p2.x; p2.y = (s2.y <= -1e29f) ? 0.f : p2.y; }
;             rs2 += p2;
;             P[i >> 3][i & 7] = (half_t)p2.x;
;             P[i >> 3][(i & 7) + 1] = (half_t)p2.y;
;           }
;           lrun[qg] += rs2.x + rs2.y;
.Leager_gqa_3:
	s_nop 7
	v_mfma_f32_32x32x16_f16 v[66:81], v[198:201], v[114:117], 0
	v_mfma_f32_32x32x16_f16 v[66:81], v[202:205], v[118:121], v[66:81]
	v_mfma_f32_32x32x16_f16 v[66:81], v[206:209], v[122:125], v[66:81]
	v_mfma_f32_32x32x16_f16 v[66:81], v[210:213], v[126:129], v[66:81]
	s_nop 15
	s_nop 15
	v_max3_f32 v232, v66, v67, v68
	v_max3_f32 v233, v69, v70, v71
	v_max3_f32 v232, v232, v72, v73
	v_max3_f32 v232, v232, v76, v77
	v_max3_f32 v232, v232, v80, v81
	v_max3_f32 v233, v233, v74, v75
	v_max3_f32 v233, v233, v78, v79
	v_max_f32_e32 v232, v232, v233
	v_mov_b32_e32 v233, v232
	s_nop 1
	v_permlane32_swap_b32_e32 v233, v232
	v_max_f32_e32 v232, v232, v233
	v_max_f32_e32 v233, v196, v232
	v_sub_f32_e32 v230, v196, v233
	v_exp_f32_e32 v230, v230
	v_mov_b32_e32 v196, v233
	v_mul_f32_e32 v1, v1, v230
	v_pk_mul_f32 v[34:35], v[34:35], v[230:231] op_sel_hi:[1,0]
	v_pk_mul_f32 v[36:37], v[36:37], v[230:231] op_sel_hi:[1,0]
	v_pk_mul_f32 v[38:39], v[38:39], v[230:231] op_sel_hi:[1,0]
	v_pk_mul_f32 v[40:41], v[40:41], v[230:231] op_sel_hi:[1,0]
	v_pk_mul_f32 v[42:43], v[42:43], v[230:231] op_sel_hi:[1,0]
	v_pk_mul_f32 v[44:45], v[44:45], v[230:231] op_sel_hi:[1,0]
	v_pk_mul_f32 v[46:47], v[46:47], v[230:231] op_sel_hi:[1,0]
	v_pk_mul_f32 v[48:49], v[48:49], v[230:231] op_sel_hi:[1,0]
	v_pk_mul_f32 v[50:51], v[50:51], v[230:231] op_sel_hi:[1,0]
	v_pk_mul_f32 v[52:53], v[52:53], v[230:231] op_sel_hi:[1,0]
	v_pk_mul_f32 v[54:55], v[54:55], v[230:231] op_sel_hi:[1,0]
	v_pk_mul_f32 v[56:57], v[56:57], v[230:231] op_sel_hi:[1,0]
	v_pk_mul_f32 v[58:59], v[58:59], v[230:231] op_sel_hi:[1,0]
	v_pk_mul_f32 v[60:61], v[60:61], v[230:231] op_sel_hi:[1,0]
	v_pk_mul_f32 v[62:63], v[62:63], v[230:231] op_sel_hi:[1,0]
	v_pk_mul_f32 v[64:65], v[64:65], v[230:231] op_sel_hi:[1,0]
	v_pk_add_f32 v[66:67], v[66:67], v[196:197] op_sel_hi:[1,0] neg_lo:[0,1] neg_hi:[0,1]
	v_pk_add_f32 v[68:69], v[68:69], v[196:197] op_sel_hi:[1,0] neg_lo:[0,1] neg_hi:[0,1]
	v_pk_add_f32 v[70:71], v[70:71], v[196:197] op_sel_hi:[1,0] neg_lo:[0,1] neg_hi:[0,1]
	v_pk_add_f32 v[72:73], v[72:73], v[196:197] op_sel_hi:[1,0] neg_lo:[0,1] neg_hi:[0,1]
	v_pk_add_f32 v[74:75], v[74:75], v[196:197] op_sel_hi:[1,0] neg_lo:[0,1] neg_hi:[0,1]
	v_pk_add_f32 v[76:77], v[76:77], v[196:197] op_sel_hi:[1,0] neg_lo:[0,1] neg_hi:[0,1]
	v_pk_add_f32 v[78:79], v[78:79], v[196:197] op_sel_hi:[1,0] neg_lo:[0,1] neg_hi:[0,1]
	v_pk_add_f32 v[80:81], v[80:81], v[196:197] op_sel_hi:[1,0] neg_lo:[0,1] neg_hi:[0,1]
	v_exp_f32_e32 v66, v66
	v_exp_f32_e32 v67, v67
	v_exp_f32_e32 v68, v68
	v_exp_f32_e32 v69, v69
	v_exp_f32_e32 v70, v70
	v_exp_f32_e32 v71, v71
	v_exp_f32_e32 v72, v72
	v_exp_f32_e32 v73, v73
	v_exp_f32_e32 v74, v74
	v_exp_f32_e32 v75, v75
	v_exp_f32_e32 v76, v76
	v_exp_f32_e32 v77, v77
	v_exp_f32_e32 v78, v78
	v_exp_f32_e32 v79, v79
	v_exp_f32_e32 v80, v80
	v_exp_f32_e32 v81, v81
	s_nop 0
	v_cvt_pk_f16_f32 v214, v66, v67
	v_cvt_pk_f16_f32 v215, v68, v69
	v_cvt_pk_f16_f32 v216, v70, v71
	v_cvt_pk_f16_f32 v217, v72, v73
	v_cvt_pk_f16_f32 v218, v74, v75
	v_cvt_pk_f16_f32 v219, v76, v77
	v_cvt_pk_f16_f32 v220, v78, v79
	v_cvt_pk_f16_f32 v221, v80, v81
	v_pk_add_f32 v[222:223], v[66:67], v[68:69]
	v_pk_add_f32 v[224:225], v[70:71], v[72:73]
	v_pk_add_f32 v[226:227], v[74:75], v[76:77]
	v_pk_add_f32 v[228:229], v[78:79], v[80:81]
	v_pk_add_f32 v[222:223], v[222:223], v[224:225]
	v_pk_add_f32 v[226:227], v[226:227], v[228:229]
	v_pk_add_f32 v[222:223], v[222:223], v[226:227]
	v_add_f32_e32 v222, v222, v223
	s_branch .Lcont_gqa_3
